# v98 with eight evenly spaced start-offset classes (bit1 +72, bit0 +145, second group +286 sleep units) instead of four
# speedup vs baseline: 1.0029x; 1.0029x over previous
; #define SW_BEGIN(id) unsigned long long sw_t0_##id = 0; if (SW_ID == (id)) sw_t0_##id = __builtin_amdgcn_s_memrealtime()
; #define SW_BEGIN(id) do {} while (0)
; #define GAS __attribute__((address_space(1)))
; __global__ void __launch_bounds__(NWAVES * 64, 2) hybrid_fwd(Args args) {
;     ...
;             pg8::Gemm g{(const f16*)XB, (const f16*)WIN + (size_t)l * PW * DM, MROWS, PW, DM}; pg8::StaticOrder S; S.init(MROWS, PW, G, bx, G1_CPERM, cls ? 1 : 0);
;             pg8::EpiProj E{PROJ, PROJ + (size_t)MROWS * KVW, PART, (const GAS float*)q_norm_g + l * 64, (const GAS float*)k_norm_g + l * 64, lds + RING_BYTES};
;             if (cls && l == 0 && (bx & 1)) asm volatile("s_sleep 127\n\ts_sleep 64" ::: "memory");
;             if (cls && l == 0 && (bx >> 7)) asm volatile("s_sleep 127\n\ts_sleep 127\n\ts_sleep 127" ::: "memory");
;             SW_BEGIN(5);
;             pg8::gemm_phase<pg8::EpiProj>(lds + RING_OFF, g, S, E, sw_acc);
.LBB0_101:
	v_readlane_b32 s0, v252, 3
	v_readlane_b32 s36, v252, 9
	v_readlane_b32 s1, v252, 4
	v_readlane_b32 s37, v252, 10
	v_readlane_b32 s44, v252, 17
	v_readlane_b32 s45, v252, 18
	v_readlane_b32 s46, v252, 19
	v_readlane_b32 s47, v252, 20
	v_readlane_b32 s38, v252, 11
	v_readlane_b32 s39, v252, 12
	v_readlane_b32 s40, v252, 13
	v_readlane_b32 s41, v252, 14
	v_readlane_b32 s42, v252, 15
	v_readlane_b32 s43, v252, 16
	v_readlane_b32 s48, v252, 21
	v_readlane_b32 s49, v252, 22
	v_readlane_b32 s50, v252, 23
	v_readlane_b32 s51, v252, 24
	v_writelane_b32 v250, s0, 0
	v_writelane_b32 v252, s36, 9
	s_nop 0
	v_writelane_b32 v250, s1, 1
	v_readlane_b32 s0, v251, 36
	v_writelane_b32 v252, s37, 10
	v_writelane_b32 v252, s38, 11
	v_writelane_b32 v252, s39, 12
	v_writelane_b32 v252, s40, 13
	v_writelane_b32 v252, s41, 14
	v_writelane_b32 v252, s42, 15
	v_writelane_b32 v252, s43, 16
	v_writelane_b32 v252, s44, 17
	v_writelane_b32 v252, s45, 18
	v_writelane_b32 v252, s46, 19
	v_writelane_b32 v252, s47, 20
	v_writelane_b32 v252, s48, 21
	v_writelane_b32 v252, s49, 22
	v_writelane_b32 v252, s50, 23
	v_writelane_b32 v252, s51, 24
	v_readlane_b32 s1, v251, 37
	s_and_b64 s[4:5], s[0:1], s[6:7]
	v_readlane_b32 s0, v252, 25
	v_readlane_b32 s1, v252, 26
	s_and_b64 s[0:1], s[0:1], s[4:5]
	s_andn2_b64 vcc, exec, s[0:1]
	v_readlane_b32 s0, v252, 5
	v_readlane_b32 s1, v252, 6
	s_nop 0
	v_writelane_b32 v252, s0, 5
	s_nop 1
	v_writelane_b32 v252, s1, 6
	s_cbranch_vccnz .LBB0_103
	s_sleep 127
	s_sleep 18
.LBB0_103:
	v_readlane_b32 s0, v252, 27
	v_readlane_b32 s1, v252, 28
	s_and_b64 s[0:1], s[0:1], s[4:5]
	v_writelane_b32 v250, s6, 2
	s_andn2_b64 vcc, exec, s[0:1]
	s_nop 0
	v_writelane_b32 v250, s7, 3
	s_cbranch_vccnz .LBB0_105
	s_sleep 127
	s_sleep 127
	s_sleep 32
.LBB0_105:
	v_readlane_b32 s0, v252, 2
	s_and_b64 vcc, exec, s[4:5]
	s_cbranch_vccz .Loff3_skip
	s_bitcmp1_b32 s0, 1
	s_cbranch_scc0 .Loff3_skip
	s_sleep 72
